# GEMM phase entry: the sums-of-squares loads behind the per-unit rstd table are issued for all units first (own registers each), waited once, then reduced - instead of one cold load round trip per unit
# baseline (speedup 1.0000x reference)
.LBB0_467:
	s_waitcnt vmcnt(0)
	s_cmp_ge_i32 s26, s24
	s_cbranch_scc1 .Lmy_rs_c0
	s_ashr_i32 s28, s26, 31
	s_lshr_b32 s28, s28, 29
	s_add_i32 s28, s26, s28
	s_ashr_i32 s29, s28, 3
	s_and_b32 s28, s28, -8
	s_sub_i32 s28, s26, s28
	s_lshr_b32 s37, s28, 31
	s_or_b32 s37, s30, s37
	s_mul_i32 s28, s37, s28
	s_add_i32 s28, s28, s29
	s_abs_i32 s37, s28
	s_mul_hi_u32 s42, s37, s13
	s_mul_i32 s43, s42, s30
	s_sub_i32 s37, s37, s43
	s_ashr_i32 s29, s28, 31
	s_add_i32 s43, s42, 1
	s_sub_i32 s44, s37, s30
	s_cmp_ge_u32 s37, s30
	s_cselect_b32 s42, s43, s42
	s_cselect_b32 s37, s44, s37
	s_add_i32 s43, s42, 1
	s_cmp_ge_u32 s37, s30
	s_cselect_b32 s37, s43, s42
	s_xor_b32 s37, s37, s29
	s_sub_i32 s29, s37, s29
	s_lshl_b32 s37, s29, 3
	s_sub_i32 s42, 64, s37
	s_min_i32 s42, s42, 8
	s_abs_i32 s42, s42
	v_cvt_f32_u32_e32 v1, s42
	s_sub_i32 s43, 0, s42
	s_mul_i32 s29, s29, s30
	s_sub_i32 s28, s28, s29
	v_rcp_iflag_f32_e32 v1, v1
	s_ashr_i32 s29, s28, 31
	s_abs_i32 s28, s28
	v_mul_f32_e32 v1, 0x4f7ffffe, v1
	v_cvt_u32_f32_e32 v1, v1
	s_nop 0
	v_readfirstlane_b32 s44, v1
	s_mul_i32 s43, s43, s44
	s_mul_hi_u32 s43, s44, s43
	s_add_i32 s44, s44, s43
	s_mul_hi_u32 s43, s28, s44
	s_mul_i32 s43, s43, s42
	s_sub_i32 s28, s28, s43
	s_sub_i32 s43, s28, s42
	s_cmp_ge_u32 s28, s42
	s_cselect_b32 s28, s43, s28
	s_sub_i32 s43, s28, s42
	s_cmp_ge_u32 s28, s42
	s_cselect_b32 s28, s43, s28
	s_xor_b32 s28, s28, s29
	s_sub_i32 s28, s28, s29
	s_add_i32 s50, s28, s37
	s_and_saveexec_b64 s[28:29], s[40:41]
	s_cbranch_execz .Lmy_rs_i0
	v_lshl_add_u32 v20, s50, 8, v164
	v_ashrrev_i32_e32 v21, 31, v20
	v_lshlrev_b64 v[20:21], 6, v[20:21]
	v_lshl_add_u64 v[32:33], s[14:15], 0, v[20:21]
	global_load_dwordx4 v[20:23], v[32:33], off
	global_load_dwordx4 v[24:27], v[32:33], off offset:32
	global_load_dwordx4 v[28:31], v[32:33], off offset:16
	global_load_dwordx4 v[32:35], v[32:33], off offset:48
.Lmy_rs_i0:
	s_or_b64 exec, exec, s[28:29]
	s_add_u32 s26, s26, s80
	s_addc_u32 s27, s27, s31
	s_cmp_ge_i32 s26, s24
	s_cbranch_scc1 .Lmy_rs_c1
	s_ashr_i32 s28, s26, 31
	s_lshr_b32 s28, s28, 29
	s_add_i32 s28, s26, s28
	s_ashr_i32 s29, s28, 3
	s_and_b32 s28, s28, -8
	s_sub_i32 s28, s26, s28
	s_lshr_b32 s37, s28, 31
	s_or_b32 s37, s30, s37
	s_mul_i32 s28, s37, s28
	s_add_i32 s28, s28, s29
	s_abs_i32 s37, s28
	s_mul_hi_u32 s42, s37, s13
	s_mul_i32 s43, s42, s30
	s_sub_i32 s37, s37, s43
	s_ashr_i32 s29, s28, 31
	s_add_i32 s43, s42, 1
	s_sub_i32 s44, s37, s30
	s_cmp_ge_u32 s37, s30
	s_cselect_b32 s42, s43, s42
	s_cselect_b32 s37, s44, s37
	s_add_i32 s43, s42, 1
	s_cmp_ge_u32 s37, s30
	s_cselect_b32 s37, s43, s42
	s_xor_b32 s37, s37, s29
	s_sub_i32 s29, s37, s29
	s_lshl_b32 s37, s29, 3
	s_sub_i32 s42, 64, s37
	s_min_i32 s42, s42, 8
	s_abs_i32 s42, s42
	v_cvt_f32_u32_e32 v1, s42
	s_sub_i32 s43, 0, s42
	s_mul_i32 s29, s29, s30
	s_sub_i32 s28, s28, s29
	v_rcp_iflag_f32_e32 v1, v1
	s_ashr_i32 s29, s28, 31
	s_abs_i32 s28, s28
	v_mul_f32_e32 v1, 0x4f7ffffe, v1
	v_cvt_u32_f32_e32 v1, v1
	s_nop 0
	v_readfirstlane_b32 s44, v1
	s_mul_i32 s43, s43, s44
	s_mul_hi_u32 s43, s44, s43
	s_add_i32 s44, s44, s43
	s_mul_hi_u32 s43, s28, s44
	s_mul_i32 s43, s43, s42
	s_sub_i32 s28, s28, s43
	s_sub_i32 s43, s28, s42
	s_cmp_ge_u32 s28, s42
	s_cselect_b32 s28, s43, s28
	s_sub_i32 s43, s28, s42
	s_cmp_ge_u32 s28, s42
	s_cselect_b32 s28, s43, s28
	s_xor_b32 s28, s28, s29
	s_sub_i32 s28, s28, s29
	s_add_i32 s50, s28, s37
	s_and_saveexec_b64 s[28:29], s[40:41]
	s_cbranch_execz .Lmy_rs_i1
	v_lshl_add_u32 v38, s50, 8, v164
	v_ashrrev_i32_e32 v39, 31, v38
	v_lshlrev_b64 v[38:39], 6, v[38:39]
	v_lshl_add_u64 v[50:51], s[14:15], 0, v[38:39]
	global_load_dwordx4 v[38:41], v[50:51], off
	global_load_dwordx4 v[42:45], v[50:51], off offset:32
	global_load_dwordx4 v[46:49], v[50:51], off offset:16
	global_load_dwordx4 v[50:53], v[50:51], off offset:48
.Lmy_rs_i1:
	s_or_b64 exec, exec, s[28:29]
	s_add_u32 s26, s26, s80
	s_addc_u32 s27, s27, s31
	s_cmp_ge_i32 s26, s24
	s_cbranch_scc1 .Lmy_rs_c2
	s_ashr_i32 s28, s26, 31
	s_lshr_b32 s28, s28, 29
	s_add_i32 s28, s26, s28
	s_ashr_i32 s29, s28, 3
	s_and_b32 s28, s28, -8
	s_sub_i32 s28, s26, s28
	s_lshr_b32 s37, s28, 31
	s_or_b32 s37, s30, s37
	s_mul_i32 s28, s37, s28
	s_add_i32 s28, s28, s29
	s_abs_i32 s37, s28
	s_mul_hi_u32 s42, s37, s13
	s_mul_i32 s43, s42, s30
	s_sub_i32 s37, s37, s43
	s_ashr_i32 s29, s28, 31
	s_add_i32 s43, s42, 1
	s_sub_i32 s44, s37, s30
	s_cmp_ge_u32 s37, s30
	s_cselect_b32 s42, s43, s42
	s_cselect_b32 s37, s44, s37
	s_add_i32 s43, s42, 1
	s_cmp_ge_u32 s37, s30
	s_cselect_b32 s37, s43, s42
	s_xor_b32 s37, s37, s29
	s_sub_i32 s29, s37, s29
	s_lshl_b32 s37, s29, 3
	s_sub_i32 s42, 64, s37
	s_min_i32 s42, s42, 8
	s_abs_i32 s42, s42
	v_cvt_f32_u32_e32 v1, s42
	s_sub_i32 s43, 0, s42
	s_mul_i32 s29, s29, s30
	s_sub_i32 s28, s28, s29
	v_rcp_iflag_f32_e32 v1, v1
	s_ashr_i32 s29, s28, 31
	s_abs_i32 s28, s28
	v_mul_f32_e32 v1, 0x4f7ffffe, v1
	v_cvt_u32_f32_e32 v1, v1
	s_nop 0
	v_readfirstlane_b32 s44, v1
	s_mul_i32 s43, s43, s44
	s_mul_hi_u32 s43, s44, s43
	s_add_i32 s44, s44, s43
	s_mul_hi_u32 s43, s28, s44
	s_mul_i32 s43, s43, s42
	s_sub_i32 s28, s28, s43
	s_sub_i32 s43, s28, s42
	s_cmp_ge_u32 s28, s42
	s_cselect_b32 s28, s43, s28
	s_sub_i32 s43, s28, s42
	s_cmp_ge_u32 s28, s42
	s_cselect_b32 s28, s43, s28
	s_xor_b32 s28, s28, s29
	s_sub_i32 s28, s28, s29
	s_add_i32 s50, s28, s37
	s_and_saveexec_b64 s[28:29], s[40:41]
	s_cbranch_execz .Lmy_rs_i2
	v_lshl_add_u32 v56, s50, 8, v164
	v_ashrrev_i32_e32 v57, 31, v56
	v_lshlrev_b64 v[56:57], 6, v[56:57]
	v_lshl_add_u64 v[68:69], s[14:15], 0, v[56:57]
	global_load_dwordx4 v[56:59], v[68:69], off
	global_load_dwordx4 v[60:63], v[68:69], off offset:32
	global_load_dwordx4 v[64:67], v[68:69], off offset:16
	global_load_dwordx4 v[68:71], v[68:69], off offset:48
.Lmy_rs_i2:
	s_or_b64 exec, exec, s[28:29]
	s_add_u32 s26, s26, s80
	s_addc_u32 s27, s27, s31
	s_cmp_ge_i32 s26, s24
	s_cbranch_scc1 .Lmy_rs_c3
	s_ashr_i32 s28, s26, 31
	s_lshr_b32 s28, s28, 29
	s_add_i32 s28, s26, s28
	s_ashr_i32 s29, s28, 3
	s_and_b32 s28, s28, -8
	s_sub_i32 s28, s26, s28
	s_lshr_b32 s37, s28, 31
	s_or_b32 s37, s30, s37
	s_mul_i32 s28, s37, s28
	s_add_i32 s28, s28, s29
	s_abs_i32 s37, s28
	s_mul_hi_u32 s42, s37, s13
	s_mul_i32 s43, s42, s30
	s_sub_i32 s37, s37, s43
	s_ashr_i32 s29, s28, 31
	s_add_i32 s43, s42, 1
	s_sub_i32 s44, s37, s30
	s_cmp_ge_u32 s37, s30
	s_cselect_b32 s42, s43, s42
	s_cselect_b32 s37, s44, s37
	s_add_i32 s43, s42, 1
	s_cmp_ge_u32 s37, s30
	s_cselect_b32 s37, s43, s42
	s_xor_b32 s37, s37, s29
	s_sub_i32 s29, s37, s29
	s_lshl_b32 s37, s29, 3
	s_sub_i32 s42, 64, s37
	s_min_i32 s42, s42, 8
	s_abs_i32 s42, s42
	v_cvt_f32_u32_e32 v1, s42
	s_sub_i32 s43, 0, s42
	s_mul_i32 s29, s29, s30
	s_sub_i32 s28, s28, s29
	v_rcp_iflag_f32_e32 v1, v1
	s_ashr_i32 s29, s28, 31
	s_abs_i32 s28, s28
	v_mul_f32_e32 v1, 0x4f7ffffe, v1
	v_cvt_u32_f32_e32 v1, v1
	s_nop 0
	v_readfirstlane_b32 s44, v1
	s_mul_i32 s43, s43, s44
	s_mul_hi_u32 s43, s44, s43
	s_add_i32 s44, s44, s43
	s_mul_hi_u32 s43, s28, s44
	s_mul_i32 s43, s43, s42
	s_sub_i32 s28, s28, s43
	s_sub_i32 s43, s28, s42
	s_cmp_ge_u32 s28, s42
	s_cselect_b32 s28, s43, s28
	s_sub_i32 s43, s28, s42
	s_cmp_ge_u32 s28, s42
	s_cselect_b32 s28, s43, s28
	s_xor_b32 s28, s28, s29
	s_sub_i32 s28, s28, s29
	s_add_i32 s50, s28, s37
	s_and_saveexec_b64 s[28:29], s[40:41]
	s_cbranch_execz .Lmy_rs_i3
	v_lshl_add_u32 v74, s50, 8, v164
	v_ashrrev_i32_e32 v75, 31, v74
	v_lshlrev_b64 v[74:75], 6, v[74:75]
	v_lshl_add_u64 v[86:87], s[14:15], 0, v[74:75]
	global_load_dwordx4 v[74:77], v[86:87], off
	global_load_dwordx4 v[78:81], v[86:87], off offset:32
	global_load_dwordx4 v[82:85], v[86:87], off offset:16
	global_load_dwordx4 v[86:89], v[86:87], off offset:48
.Lmy_rs_i3:
	s_or_b64 exec, exec, s[28:29]
	s_add_u32 s26, s26, s80
	s_addc_u32 s27, s27, s31
	s_cmp_ge_i32 s26, s24
	s_cbranch_scc1 .Lmy_rs_c4
	s_ashr_i32 s28, s26, 31
	s_lshr_b32 s28, s28, 29
	s_add_i32 s28, s26, s28
	s_ashr_i32 s29, s28, 3
	s_and_b32 s28, s28, -8
	s_sub_i32 s28, s26, s28
	s_lshr_b32 s37, s28, 31
	s_or_b32 s37, s30, s37
	s_mul_i32 s28, s37, s28
	s_add_i32 s28, s28, s29
	s_abs_i32 s37, s28
	s_mul_hi_u32 s42, s37, s13
	s_mul_i32 s43, s42, s30
	s_sub_i32 s37, s37, s43
	s_ashr_i32 s29, s28, 31
	s_add_i32 s43, s42, 1
	s_sub_i32 s44, s37, s30
	s_cmp_ge_u32 s37, s30
	s_cselect_b32 s42, s43, s42
	s_cselect_b32 s37, s44, s37
	s_add_i32 s43, s42, 1
	s_cmp_ge_u32 s37, s30
	s_cselect_b32 s37, s43, s42
	s_xor_b32 s37, s37, s29
	s_sub_i32 s29, s37, s29
	s_lshl_b32 s37, s29, 3
	s_sub_i32 s42, 64, s37
	s_min_i32 s42, s42, 8
	s_abs_i32 s42, s42
	v_cvt_f32_u32_e32 v1, s42
	s_sub_i32 s43, 0, s42
	s_mul_i32 s29, s29, s30
	s_sub_i32 s28, s28, s29
	v_rcp_iflag_f32_e32 v1, v1
	s_ashr_i32 s29, s28, 31
	s_abs_i32 s28, s28
	v_mul_f32_e32 v1, 0x4f7ffffe, v1
	v_cvt_u32_f32_e32 v1, v1
	s_nop 0
	v_readfirstlane_b32 s44, v1
	s_mul_i32 s43, s43, s44
	s_mul_hi_u32 s43, s44, s43
	s_add_i32 s44, s44, s43
	s_mul_hi_u32 s43, s28, s44
	s_mul_i32 s43, s43, s42
	s_sub_i32 s28, s28, s43
	s_sub_i32 s43, s28, s42
	s_cmp_ge_u32 s28, s42
	s_cselect_b32 s28, s43, s28
	s_sub_i32 s43, s28, s42
	s_cmp_ge_u32 s28, s42
	s_cselect_b32 s28, s43, s28
	s_xor_b32 s28, s28, s29
	s_sub_i32 s28, s28, s29
	s_add_i32 s50, s28, s37
	s_and_saveexec_b64 s[28:29], s[40:41]
	s_cbranch_execz .Lmy_rs_i4
	v_lshl_add_u32 v92, s50, 8, v164
	v_ashrrev_i32_e32 v93, 31, v92
	v_lshlrev_b64 v[92:93], 6, v[92:93]
	v_lshl_add_u64 v[104:105], s[14:15], 0, v[92:93]
	global_load_dwordx4 v[92:95], v[104:105], off
	global_load_dwordx4 v[96:99], v[104:105], off offset:32
	global_load_dwordx4 v[100:103], v[104:105], off offset:16
	global_load_dwordx4 v[104:107], v[104:105], off offset:48
.Lmy_rs_i4:
	s_or_b64 exec, exec, s[28:29]
	s_add_u32 s26, s26, s80
	s_addc_u32 s27, s27, s31
	s_cmp_ge_i32 s26, s24
	s_cbranch_scc1 .Lmy_rs_c5
	s_ashr_i32 s28, s26, 31
	s_lshr_b32 s28, s28, 29
	s_add_i32 s28, s26, s28
	s_ashr_i32 s29, s28, 3
	s_and_b32 s28, s28, -8
	s_sub_i32 s28, s26, s28
	s_lshr_b32 s37, s28, 31
	s_or_b32 s37, s30, s37
	s_mul_i32 s28, s37, s28
	s_add_i32 s28, s28, s29
	s_abs_i32 s37, s28
	s_mul_hi_u32 s42, s37, s13
	s_mul_i32 s43, s42, s30
	s_sub_i32 s37, s37, s43
	s_ashr_i32 s29, s28, 31
	s_add_i32 s43, s42, 1
	s_sub_i32 s44, s37, s30
	s_cmp_ge_u32 s37, s30
	s_cselect_b32 s42, s43, s42
	s_cselect_b32 s37, s44, s37
	s_add_i32 s43, s42, 1
	s_cmp_ge_u32 s37, s30
	s_cselect_b32 s37, s43, s42
	s_xor_b32 s37, s37, s29
	s_sub_i32 s29, s37, s29
	s_lshl_b32 s37, s29, 3
	s_sub_i32 s42, 64, s37
	s_min_i32 s42, s42, 8
	s_abs_i32 s42, s42
	v_cvt_f32_u32_e32 v1, s42
	s_sub_i32 s43, 0, s42
	s_mul_i32 s29, s29, s30
	s_sub_i32 s28, s28, s29
	v_rcp_iflag_f32_e32 v1, v1
	s_ashr_i32 s29, s28, 31
	s_abs_i32 s28, s28
	v_mul_f32_e32 v1, 0x4f7ffffe, v1
	v_cvt_u32_f32_e32 v1, v1
	s_nop 0
	v_readfirstlane_b32 s44, v1
	s_mul_i32 s43, s43, s44
	s_mul_hi_u32 s43, s44, s43
	s_add_i32 s44, s44, s43
	s_mul_hi_u32 s43, s28, s44
	s_mul_i32 s43, s43, s42
	s_sub_i32 s28, s28, s43
	s_sub_i32 s43, s28, s42
	s_cmp_ge_u32 s28, s42
	s_cselect_b32 s28, s43, s28
	s_sub_i32 s43, s28, s42
	s_cmp_ge_u32 s28, s42
	s_cselect_b32 s28, s43, s28
	s_xor_b32 s28, s28, s29
	s_sub_i32 s28, s28, s29
	s_add_i32 s50, s28, s37
	s_and_saveexec_b64 s[28:29], s[40:41]
	s_cbranch_execz .Lmy_rs_i5
	v_lshl_add_u32 v110, s50, 8, v164
	v_ashrrev_i32_e32 v111, 31, v110
	v_lshlrev_b64 v[110:111], 6, v[110:111]
	v_lshl_add_u64 v[122:123], s[14:15], 0, v[110:111]
	global_load_dwordx4 v[110:113], v[122:123], off
	global_load_dwordx4 v[114:117], v[122:123], off offset:32
	global_load_dwordx4 v[118:121], v[122:123], off offset:16
	global_load_dwordx4 v[122:125], v[122:123], off offset:48
.Lmy_rs_i5:
	s_or_b64 exec, exec, s[28:29]
	s_add_u32 s26, s26, s80
	s_addc_u32 s27, s27, s31
.Lmy_rs_c6:
	s_and_saveexec_b64 s[28:29], s[40:41]
	s_cbranch_execz .Lmy_rs_e6
	s_waitcnt vmcnt(0)
	v_mov_b32_e32 v126, v110
	v_mov_b32_e32 v127, v114
	v_mov_b32_e32 v114, v111
	v_mov_b32_e32 v110, v112
	v_mov_b32_e32 v111, v116
	v_mov_b32_e32 v116, v113
	v_mov_b32_e32 v112, v118
	v_mov_b32_e32 v113, v122
	v_mov_b32_e32 v122, v119
	v_mov_b32_e32 v118, v120
	v_mov_b32_e32 v119, v124
	v_mov_b32_e32 v124, v121
	v_pk_add_f32 v[114:115], v[126:127], v[114:115]
	v_pk_add_f32 v[110:111], v[110:111], v[116:117]
	v_pk_add_f32 v[112:113], v[112:113], v[122:123]
	v_pk_add_f32 v[116:117], v[118:119], v[124:125]
	v_pk_add_f32 v[110:111], v[114:115], v[110:111]
	v_pk_add_f32 v[112:113], v[112:113], v[116:117]
	s_nop 0
	v_pk_add_f32 v[110:111], v[110:111], v[112:113]
	s_nop 0
	v_add_f32_e32 v1, v110, v111
	v_fmamk_f32 v1, v1, 0x3a800000, v209
	v_rsq_f32_e32 v1, v1
	v_add_u32_e32 v110, 0x1400, v0
	ds_write_b32 v110, v1

.Lmy_rs_c5:
	s_and_saveexec_b64 s[28:29], s[40:41]
	s_cbranch_execz .Lmy_rs_e5
	s_waitcnt vmcnt(0)
	v_mov_b32_e32 v108, v92
	v_mov_b32_e32 v109, v96
	v_mov_b32_e32 v96, v93
	v_mov_b32_e32 v92, v94
	v_mov_b32_e32 v93, v98
	v_mov_b32_e32 v98, v95
	v_mov_b32_e32 v94, v100
	v_mov_b32_e32 v95, v104
	v_mov_b32_e32 v104, v101
	v_mov_b32_e32 v100, v102
	v_mov_b32_e32 v101, v106
	v_mov_b32_e32 v106, v103
	v_pk_add_f32 v[96:97], v[108:109], v[96:97]
	v_pk_add_f32 v[92:93], v[92:93], v[98:99]
	v_pk_add_f32 v[94:95], v[94:95], v[104:105]
	v_pk_add_f32 v[98:99], v[100:101], v[106:107]
	v_pk_add_f32 v[92:93], v[96:97], v[92:93]
	v_pk_add_f32 v[94:95], v[94:95], v[98:99]
	s_nop 0
	v_pk_add_f32 v[92:93], v[92:93], v[94:95]
	s_nop 0
	v_add_f32_e32 v1, v92, v93
	v_fmamk_f32 v1, v1, 0x3a800000, v209
	v_rsq_f32_e32 v1, v1
	v_add_u32_e32 v92, 0x1000, v0
	ds_write_b32 v92, v1

.Lmy_rs_c4:
	s_and_saveexec_b64 s[28:29], s[40:41]
	s_cbranch_execz .Lmy_rs_e4
	s_waitcnt vmcnt(0)
	v_mov_b32_e32 v90, v74
	v_mov_b32_e32 v91, v78
	v_mov_b32_e32 v78, v75
	v_mov_b32_e32 v74, v76
	v_mov_b32_e32 v75, v80
	v_mov_b32_e32 v80, v77
	v_mov_b32_e32 v76, v82
	v_mov_b32_e32 v77, v86
	v_mov_b32_e32 v86, v83
	v_mov_b32_e32 v82, v84
	v_mov_b32_e32 v83, v88
	v_mov_b32_e32 v88, v85
	v_pk_add_f32 v[78:79], v[90:91], v[78:79]
	v_pk_add_f32 v[74:75], v[74:75], v[80:81]
	v_pk_add_f32 v[76:77], v[76:77], v[86:87]
	v_pk_add_f32 v[80:81], v[82:83], v[88:89]
	v_pk_add_f32 v[74:75], v[78:79], v[74:75]
	v_pk_add_f32 v[76:77], v[76:77], v[80:81]
	s_nop 0
	v_pk_add_f32 v[74:75], v[74:75], v[76:77]
	s_nop 0
	v_add_f32_e32 v1, v74, v75
	v_fmamk_f32 v1, v1, 0x3a800000, v209
	v_rsq_f32_e32 v1, v1
	v_add_u32_e32 v74, 0xc00, v0
	ds_write_b32 v74, v1

.Lmy_rs_c3:
	s_and_saveexec_b64 s[28:29], s[40:41]
	s_cbranch_execz .Lmy_rs_e3
	s_waitcnt vmcnt(0)
	v_mov_b32_e32 v72, v56
	v_mov_b32_e32 v73, v60
	v_mov_b32_e32 v60, v57
	v_mov_b32_e32 v56, v58
	v_mov_b32_e32 v57, v62
	v_mov_b32_e32 v62, v59
	v_mov_b32_e32 v58, v64
	v_mov_b32_e32 v59, v68
	v_mov_b32_e32 v68, v65
	v_mov_b32_e32 v64, v66
	v_mov_b32_e32 v65, v70
	v_mov_b32_e32 v70, v67
	v_pk_add_f32 v[60:61], v[72:73], v[60:61]
	v_pk_add_f32 v[56:57], v[56:57], v[62:63]
	v_pk_add_f32 v[58:59], v[58:59], v[68:69]
	v_pk_add_f32 v[62:63], v[64:65], v[70:71]
	v_pk_add_f32 v[56:57], v[60:61], v[56:57]
	v_pk_add_f32 v[58:59], v[58:59], v[62:63]
	s_nop 0
	v_pk_add_f32 v[56:57], v[56:57], v[58:59]
	s_nop 0
	v_add_f32_e32 v1, v56, v57
	v_fmamk_f32 v1, v1, 0x3a800000, v209
	v_rsq_f32_e32 v1, v1
	v_add_u32_e32 v56, 0x800, v0
	ds_write_b32 v56, v1

.Lmy_rs_c2:
	s_and_saveexec_b64 s[28:29], s[40:41]
	s_cbranch_execz .Lmy_rs_e2
	s_waitcnt vmcnt(0)
	v_mov_b32_e32 v54, v38
	v_mov_b32_e32 v55, v42
	v_mov_b32_e32 v42, v39
	v_mov_b32_e32 v38, v40
	v_mov_b32_e32 v39, v44
	v_mov_b32_e32 v44, v41
	v_mov_b32_e32 v40, v46
	v_mov_b32_e32 v41, v50
	v_mov_b32_e32 v50, v47
	v_mov_b32_e32 v46, v48
	v_mov_b32_e32 v47, v52
	v_mov_b32_e32 v52, v49
	v_pk_add_f32 v[42:43], v[54:55], v[42:43]
	v_pk_add_f32 v[38:39], v[38:39], v[44:45]
	v_pk_add_f32 v[40:41], v[40:41], v[50:51]
	v_pk_add_f32 v[44:45], v[46:47], v[52:53]
	v_pk_add_f32 v[38:39], v[42:43], v[38:39]
	v_pk_add_f32 v[40:41], v[40:41], v[44:45]
	s_nop 0
	v_pk_add_f32 v[38:39], v[38:39], v[40:41]
	s_nop 0
	v_add_f32_e32 v1, v38, v39
	v_fmamk_f32 v1, v1, 0x3a800000, v209
	v_rsq_f32_e32 v1, v1
	v_add_u32_e32 v38, 0x400, v0
	ds_write_b32 v38, v1

.Lmy_rs_c1:
	s_and_saveexec_b64 s[28:29], s[40:41]
	s_cbranch_execz .Lmy_rs_e1
	s_waitcnt vmcnt(0)
	v_mov_b32_e32 v36, v20
	v_mov_b32_e32 v37, v24
	v_mov_b32_e32 v24, v21
	v_mov_b32_e32 v20, v22
	v_mov_b32_e32 v21, v26
	v_mov_b32_e32 v26, v23
	v_mov_b32_e32 v22, v28
	v_mov_b32_e32 v23, v32
	v_mov_b32_e32 v32, v29
	v_mov_b32_e32 v28, v30
	v_mov_b32_e32 v29, v34
	v_mov_b32_e32 v34, v31
	v_pk_add_f32 v[24:25], v[36:37], v[24:25]
	v_pk_add_f32 v[20:21], v[20:21], v[26:27]
	v_pk_add_f32 v[22:23], v[22:23], v[32:33]
	v_pk_add_f32 v[26:27], v[28:29], v[34:35]
	v_pk_add_f32 v[20:21], v[24:25], v[20:21]
	v_pk_add_f32 v[22:23], v[22:23], v[26:27]
	s_nop 0
	v_pk_add_f32 v[20:21], v[20:21], v[22:23]
	s_nop 0
	v_add_f32_e32 v1, v20, v21
	v_fmamk_f32 v1, v1, 0x3a800000, v209
	v_rsq_f32_e32 v1, v1
	v_add_u32_e32 v20, 0x0, v0
	ds_write_b32 v20, v1

.Lmy_rs_c0:
.LBB0_472:
	s_waitcnt lgkmcnt(0)
	s_barrier
